# all_plus_gdn_p4_rewrite_rebalanced_a5
# baseline (speedup 1.0000x reference)
.LBB0_512:
	s_or_b64 exec, exec, s[12:13]
	s_waitcnt lgkmcnt(6)
	v_lshlrev_b32_e32 v179, 16, v178
	v_lshlrev_b32_e32 v178, 16, v61
	v_lshlrev_b32_e32 v198, 1, v89
	v_pk_mul_f32 v[60:61], v[48:49], v[178:179]
	v_lshlrev_b32_e32 v179, 16, v177
	v_lshlrev_b32_e32 v178, 16, v153
	v_lshlrev_b32_e32 v153, 16, v176
	v_lshlrev_b32_e32 v176, 16, v103
	v_lshlrev_b32_e32 v103, 16, v104
	v_lshlrev_b32_e32 v102, 16, v102
	v_lshl_or_b32 v89, v109, 5, v198
	v_pk_mul_f32 v[184:185], v[52:53], v[178:179]
	v_pk_mul_f32 v[178:179], v[58:59], v[102:103]
	v_lshlrev_b32_e32 v102, 16, v100
	v_lshlrev_b32_e32 v189, 16, v101
	ds_read_u16 v190, v106 offset:7056
	ds_read_u16 v191, v106 offset:6912
	ds_read_u16 v192, v106 offset:7200
	ds_read_u16 v193, v106 offset:7344
	ds_read_u16 v194, v106 offset:7376
	ds_read_u16 v195, v106 offset:7232
	ds_read_u16 v196, v106 offset:7088
	ds_read_u16 v197, v106 offset:6944
	ds_read_b64 v[100:101], v89 offset:59392
	v_lshlrev_b32_e32 v103, 16, v105
	v_pk_mul_f32 v[186:187], v[56:57], v[102:103]
	v_mov_b32_e32 v102, v28
	v_mov_b32_e32 v103, v28
	v_lshlrev_b32_e32 v177, 16, v107
	v_pk_mul_f32 v[176:177], v[56:57], v[176:177]
	v_cvt_pk_bf16_f32 v105, v178, v179
	v_cvt_pk_bf16_f32 v104, v176, v177
	v_mov_b32_e32 v106, v28
	v_mov_b32_e32 v107, v28
	v_cndmask_b32_e64 v199, v159, v162, s[8:9]
	v_or_b32_e32 v188, v199, v198
	s_waitcnt lgkmcnt(0)
	v_mfma_f32_16x16x32_bf16 v[100:103], v[100:103], v[104:107], 0
	v_mad_u32_u24 v200, v62, s82, v188
	v_lshlrev_b32_e32 v188, 16, v96
	v_cmp_lt_u32_e64 s[8:9], 31, v167
	v_lshlrev_b32_e32 v152, 16, v152
	v_mul_f32_e32 v40, 0x3fb8aa3b, v40
	s_nop 2
	v_cvt_pk_bf16_f32 v56, v100, v101
	v_cvt_pk_bf16_f32 v57, v102, v103
	ds_write_b64 v200, v[56:57]
	ds_read_b64 v[56:57], v89 offset:59392
	v_pk_mul_f32 v[102:103], v[58:59], v[188:189]
	v_mov_b32_e32 v58, v28
	v_mov_b32_e32 v59, v28
	v_cvt_pk_bf16_f32 v100, v186, v187
	v_cvt_pk_bf16_f32 v101, v102, v103
	v_mov_b32_e32 v102, v28
	v_mov_b32_e32 v103, v28
	v_add_u32_e32 v188, v68, v88
	v_or_b32_e32 v88, v199, v68
	s_waitcnt lgkmcnt(0)
	v_mfma_f32_16x16x32_bf16 v[56:59], v[56:59], v[100:103], 0
	v_mad_u32_u24 v189, v62, s82, v88
	ds_read_b128 v[100:103], v189
	v_pk_mul_f32 v[186:187], v[54:55], v[152:153]
	v_lshl_or_b32 v88, v172, 5, v198
	v_lshlrev_b32_e32 v62, 16, v92
	s_nop 2
	v_cvt_pk_bf16_f32 v56, v56, v57
	v_cvt_pk_bf16_f32 v57, v58, v59
	ds_write_b64 v200, v[56:57] offset:2304
	ds_read_b128 v[56:59], v188 offset:48384
	ds_read_b64 v[104:105], v88 offset:59392
	ds_read_b128 v[176:179], v189 offset:2304
	v_lshlrev_b32_e32 v89, 16, v99
	v_mul_f32_e32 v41, 0x3fb8aa3b, v41
	v_mul_f32_e32 v43, 0x3fb8aa3b, v43
	s_waitcnt lgkmcnt(2)
	v_cndmask_b32_e64 v59, v59, 0, s[8:9]
	v_cndmask_b32_e64 v58, v58, 0, s[8:9]
	v_cndmask_b32_e64 v57, v57, 0, s[8:9]
	v_cndmask_b32_e64 v56, v56, 0, s[8:9]
	s_nop 1
	v_mfma_f32_16x16x32_bf16 v[56:59], v[56:59], v[100:103], v[184:187]
	v_lshlrev_b32_e32 v101, 16, v94
	v_lshlrev_b32_e32 v100, 16, v63
	v_pk_mul_f32 v[52:53], v[52:53], v[100:101]
	s_nop 4
	v_cvt_pk_bf16_f32 v56, v56, v57
	v_cvt_pk_bf16_f32 v57, v58, v59
	v_mov_b32_e32 v58, v28
	v_mov_b32_e32 v59, v28
	v_lshlrev_b32_e32 v63, 16, v93
	v_pk_mul_f32 v[54:55], v[54:55], v[62:63]
	s_waitcnt lgkmcnt(1)
	v_mfma_f32_16x16x32_bf16 v[56:59], v[104:107], v[56:59], 0
	v_mov_b32_e32 v102, v28
	v_mov_b32_e32 v103, v28
	v_mov_b32_e32 v94, v28
	s_nop 4
	v_cvt_pk_bf16_f32 v56, v56, v57
	v_cvt_pk_bf16_f32 v57, v58, v59
	ds_write_b64 v200, v[56:57] offset:32
	ds_read_b128 v[56:59], v188 offset:48384
	ds_read_b64 v[100:101], v88 offset:59392
	v_lshlrev_b32_e32 v88, 16, v97
	v_pk_mul_f32 v[62:63], v[50:51], v[88:89]
	v_lshlrev_b32_e32 v88, 16, v95
	s_waitcnt lgkmcnt(1)
	v_cndmask_b32_e64 v59, v59, 0, s[8:9]
	v_cndmask_b32_e64 v58, v58, 0, s[8:9]
	v_cndmask_b32_e64 v57, v57, 0, s[8:9]
	v_cndmask_b32_e64 v56, v56, 0, s[8:9]
	v_mov_b32_e32 v95, v28
	v_lshlrev_b32_e32 v89, 16, v98
	v_mfma_f32_16x16x32_bf16 v[52:55], v[56:59], v[176:179], v[52:55]
	ds_read_b128 v[56:59], v189
	v_pk_mul_f32 v[48:49], v[48:49], v[88:89]
	s_nop 5
	v_cvt_pk_bf16_f32 v52, v52, v53
	v_cvt_pk_bf16_f32 v53, v54, v55
	v_mov_b32_e32 v54, v28
	v_mov_b32_e32 v55, v28
	s_waitcnt lgkmcnt(1)
	s_nop 0
	v_mfma_f32_16x16x32_bf16 v[52:55], v[100:103], v[52:55], 0
	v_lshl_or_b32 v100, v173, 5, v198
	s_nop 6
	v_cvt_pk_bf16_f32 v52, v52, v53
	v_cvt_pk_bf16_f32 v53, v54, v55
	ds_write_b64 v200, v[52:53] offset:2336
	ds_read_b128 v[52:55], v188 offset:50688
	s_waitcnt lgkmcnt(0)
	v_mfma_f32_16x16x32_bf16 v[52:55], v[52:55], v[56:59], v[60:63]
	ds_read_b64 v[92:93], v100 offset:59392
	ds_read_b128 v[96:99], v189 offset:2304
	s_nop 0
	v_lshlrev_b32_e32 v61, 16, v91
	v_lshlrev_b32_e32 v60, 16, v90
	s_nop 2
	v_cvt_pk_bf16_f32 v52, v52, v53
	v_cvt_pk_bf16_f32 v53, v54, v55
	v_mov_b32_e32 v54, v28
	v_mov_b32_e32 v55, v28
	v_pk_mul_f32 v[50:51], v[50:51], v[60:61]
	v_mov_b32_e32 v90, v28
	s_waitcnt lgkmcnt(1)
	v_mfma_f32_16x16x32_bf16 v[52:55], v[92:95], v[52:55], 0
	v_mov_b32_e32 v91, v28
	v_lshlrev_b32_e32 v61, 16, v190
	v_lshlrev_b32_e32 v60, 16, v191
	v_lshlrev_b32_e32 v63, 16, v193
	v_lshlrev_b32_e32 v62, 16, v192
	s_nop 2
	v_cvt_pk_bf16_f32 v52, v52, v53
	v_cvt_pk_bf16_f32 v53, v54, v55
	ds_write_b64 v200, v[52:53] offset:64
	ds_read_b128 v[52:55], v188 offset:50688
	ds_read_b64 v[88:89], v100 offset:59392
	s_waitcnt lgkmcnt(1)
	v_mfma_f32_16x16x32_bf16 v[48:51], v[52:55], v[96:99], v[48:51]
	v_mul_f32_e64 v60, v44, v60
	v_mul_f32_e64 v61, v45, v61
	v_pk_mul_f32 v[62:63], v[46:47], v[62:63]
	v_lshl_or_b32 v92, v174, 5, v198
	s_nop 3
	v_cvt_pk_bf16_f32 v48, v48, v49
	v_cvt_pk_bf16_f32 v49, v50, v51
	v_mov_b32_e32 v50, v28
	v_mov_b32_e32 v51, v28
	s_waitcnt lgkmcnt(0)
	s_nop 0
	v_mfma_f32_16x16x32_bf16 v[48:51], v[88:91], v[48:51], 0
	s_nop 7
	v_cvt_pk_bf16_f32 v48, v48, v49
	v_cvt_pk_bf16_f32 v49, v50, v51
	ds_write_b64 v200, v[48:49] offset:2368
	ds_read_b128 v[48:51], v188 offset:52992
	ds_read_b128 v[52:55], v188 offset:53056
	ds_read_b128 v[88:91], v189 offset:64
	s_waitcnt lgkmcnt(2)
	v_mfma_f32_16x16x32_bf16 v[48:51], v[48:51], v[56:59], v[60:63]
	s_waitcnt lgkmcnt(1)
	v_cndmask_b32_e64 v55, v55, 0, s[8:9]
	v_cndmask_b32_e64 v54, v54, 0, s[8:9]
	v_cndmask_b32_e64 v53, v53, 0, s[8:9]
	v_cndmask_b32_e64 v52, v52, 0, s[8:9]
	v_mov_b32_e32 v58, v28
	v_mov_b32_e32 v59, v28
	s_waitcnt lgkmcnt(0)
	v_mfma_f32_16x16x32_bf16 v[48:51], v[52:55], v[88:91], v[48:51]
	ds_read_b64 v[56:57], v92 offset:59392
	ds_read_b128 v[60:63], v189 offset:2368
	v_lshlrev_b32_e32 v53, 16, v196
	v_lshlrev_b32_e32 v52, 16, v197
	s_nop 3
	v_cvt_pk_bf16_f32 v48, v48, v49
	v_cvt_pk_bf16_f32 v49, v50, v51
	v_mov_b32_e32 v50, v28
	v_mov_b32_e32 v51, v28
	v_pk_mul_f32 v[44:45], v[44:45], v[52:53]
	s_waitcnt lgkmcnt(1)
	v_mfma_f32_16x16x32_bf16 v[48:51], v[56:59], v[48:51], 0
	v_lshlrev_b32_e32 v57, 16, v194
	v_lshlrev_b32_e32 v56, 16, v195
	v_pk_mul_f32 v[46:47], v[46:47], v[56:57]
	s_nop 4
	v_cvt_pk_bf16_f32 v48, v48, v49
	v_cvt_pk_bf16_f32 v49, v50, v51
	ds_write_b64 v200, v[48:49] offset:96
	ds_read_b128 v[48:51], v188 offset:52992
	ds_read_b128 v[52:55], v188 offset:53056
	s_waitcnt lgkmcnt(1)
	v_mfma_f32_16x16x32_bf16 v[44:47], v[48:51], v[96:99], v[44:47]
	s_waitcnt lgkmcnt(0)
	v_cndmask_b32_e64 v51, v55, 0, s[8:9]
	v_cndmask_b32_e64 v50, v54, 0, s[8:9]
	v_cndmask_b32_e64 v49, v53, 0, s[8:9]
	v_cndmask_b32_e64 v48, v52, 0, s[8:9]
	ds_read_b64 v[52:53], v92 offset:59392
	v_mov_b32_e32 v54, v28
	v_mfma_f32_16x16x32_bf16 v[44:47], v[48:51], v[60:63], v[44:47]
	v_mov_b32_e32 v55, v28
	v_lshlrev_b32_e32 v96, 2, v78
	v_mad_u64_u32 v[152:153], s[8:9], v69, s82, v[68:69]
	s_nop 4
	v_cvt_pk_bf16_f32 v44, v44, v45
	v_cvt_pk_bf16_f32 v45, v46, v47
	v_mov_b32_e32 v46, v28
	v_mov_b32_e32 v47, v28
	s_waitcnt lgkmcnt(0)
	s_nop 0
	v_mfma_f32_16x16x32_bf16 v[44:47], v[52:55], v[44:47], 0
	s_nop 7
	v_cvt_pk_bf16_f32 v44, v44, v45
	v_cvt_pk_bf16_f32 v45, v46, v47
	ds_write_b64 v200, v[44:45] offset:2400
	s_waitcnt lgkmcnt(0)
	s_barrier
	ds_read_b128 v[44:47], v96 offset:61440
	ds_read_b128 v[48:51], v96 offset:61456
	ds_read_b128 v[52:55], v96 offset:61472
	ds_read_b128 v[56:59], v96 offset:61488
	s_waitcnt lgkmcnt(3)
	v_sub_f32_e32 v44, v111, v44
	v_mul_f32_e32 v44, 0x3fb8aa3b, v44
	v_exp_f32_e32 v60, v44
	v_sub_f32_e32 v44, v111, v45
	v_mul_f32_e32 v44, 0x3fb8aa3b, v44
	v_exp_f32_e32 v61, v44
	v_sub_f32_e32 v44, v111, v46
	v_mul_f32_e32 v44, 0x3fb8aa3b, v44
	v_exp_f32_e32 v62, v44
	v_sub_f32_e32 v44, v111, v47
	v_mul_f32_e32 v44, 0x3fb8aa3b, v44
	v_exp_f32_e32 v63, v44
	s_waitcnt lgkmcnt(2)
	v_sub_f32_e32 v44, v111, v48
	v_mul_f32_e32 v44, 0x3fb8aa3b, v44
	v_exp_f32_e32 v88, v44
	v_sub_f32_e32 v44, v111, v49
	v_mul_f32_e32 v44, 0x3fb8aa3b, v44
	v_exp_f32_e32 v89, v44
	v_sub_f32_e32 v44, v111, v50
	v_mul_f32_e32 v44, 0x3fb8aa3b, v44
	v_exp_f32_e32 v90, v44
	v_sub_f32_e32 v44, v111, v51
	v_mul_f32_e32 v44, 0x3fb8aa3b, v44
	v_exp_f32_e32 v91, v44
	s_waitcnt lgkmcnt(1)
	v_sub_f32_e32 v44, v111, v52
	v_mul_f32_e32 v44, 0x3fb8aa3b, v44
	v_exp_f32_e32 v92, v44
	v_sub_f32_e32 v44, v111, v53
	v_mul_f32_e32 v44, 0x3fb8aa3b, v44
	v_exp_f32_e32 v93, v44
	v_sub_f32_e32 v44, v111, v54
	v_mul_f32_e32 v44, 0x3fb8aa3b, v44
	v_exp_f32_e32 v94, v44
	v_sub_f32_e32 v44, v111, v55
	v_mul_f32_e32 v44, 0x3fb8aa3b, v44
	v_exp_f32_e32 v95, v44
	s_waitcnt lgkmcnt(0)
	v_sub_f32_e32 v44, v111, v56
	v_mul_f32_e32 v44, 0x3fb8aa3b, v44
	v_exp_f32_e32 v56, v44
	v_sub_f32_e32 v44, v111, v57
	v_mul_f32_e32 v44, 0x3fb8aa3b, v44
	v_exp_f32_e32 v57, v44
	v_sub_f32_e32 v44, v111, v58
	v_mul_f32_e32 v44, 0x3fb8aa3b, v44
	v_exp_f32_e32 v58, v44
	v_sub_f32_e32 v44, v111, v59
	v_mul_f32_e32 v48, 0x3fb8aa3b, v44
	ds_read_b128 v[44:47], v96 offset:61952
	v_exp_f32_e32 v59, v48
	v_mul_lo_u32 v48, v29, s92
	v_lshl_add_u32 v97, v167, 1, v48
	ds_read_b128 v[48:51], v96 offset:61968
	s_waitcnt lgkmcnt(1)
	v_pk_mul_f32 v[44:45], v[44:45], v[60:61]
	ds_read_u16 v52, v97 offset:9216
	ds_read_u16 v53, v97 offset:9360
	ds_read_u16 v54, v97 offset:9504
	ds_read_u16 v55, v97 offset:9648
	ds_read_u16 v60, v97 offset:9792
	ds_read_u16 v61, v97 offset:9936
	ds_read_u16 v98, v97 offset:10080
	ds_read_u16 v99, v97 offset:10224
	s_waitcnt lgkmcnt(6)
	v_lshlrev_b32_e32 v53, 16, v53
	v_lshlrev_b32_e32 v52, 16, v52
	v_pk_mul_f32 v[44:45], v[44:45], v[52:53]
	v_pk_mul_f32 v[46:47], v[46:47], v[62:63]
	s_waitcnt lgkmcnt(4)
	v_lshlrev_b32_e32 v53, 16, v55
	v_lshlrev_b32_e32 v52, 16, v54
	v_pk_mul_f32 v[46:47], v[46:47], v[52:53]
	v_cvt_pk_bf16_f32 v44, v44, v45
	v_cvt_pk_bf16_f32 v45, v46, v47
	v_pk_mul_f32 v[46:47], v[48:49], v[88:89]
	s_waitcnt lgkmcnt(2)
	v_lshlrev_b32_e32 v49, 16, v61
	v_lshlrev_b32_e32 v48, 16, v60
	v_pk_mul_f32 v[46:47], v[46:47], v[48:49]
	v_pk_mul_f32 v[52:53], v[50:51], v[90:91]
	ds_read_b128 v[48:51], v96 offset:61984
	s_waitcnt lgkmcnt(1)
	v_lshlrev_b32_e32 v55, 16, v99
	v_lshlrev_b32_e32 v54, 16, v98
	v_pk_mul_f32 v[52:53], v[52:53], v[54:55]
	v_cvt_pk_bf16_f32 v46, v46, v47
	v_cvt_pk_bf16_f32 v47, v52, v53
	ds_read_b128 v[52:55], v96 offset:62000
	ds_read_u16 v60, v97 offset:10368
	ds_read_u16 v61, v97 offset:10512
	ds_read_u16 v62, v97 offset:10656
	ds_read_u16 v63, v97 offset:10800
	ds_read_u16 v88, v97 offset:10944
	ds_read_u16 v89, v97 offset:11088
	ds_read_u16 v90, v97 offset:11232
	ds_read_u16 v91, v97 offset:11376
	s_waitcnt lgkmcnt(9)
	v_pk_mul_f32 v[48:49], v[48:49], v[92:93]
	s_waitcnt lgkmcnt(6)
	v_lshlrev_b32_e32 v61, 16, v61
	v_lshlrev_b32_e32 v60, 16, v60
	v_pk_mul_f32 v[48:49], v[48:49], v[60:61]
	v_pk_mul_f32 v[50:51], v[50:51], v[94:95]
	s_waitcnt lgkmcnt(4)
	v_lshlrev_b32_e32 v61, 16, v63
	v_lshlrev_b32_e32 v60, 16, v62
	v_pk_mul_f32 v[50:51], v[50:51], v[60:61]
	v_cvt_pk_bf16_f32 v48, v48, v49
	v_cvt_pk_bf16_f32 v49, v50, v51
	v_pk_mul_f32 v[50:51], v[52:53], v[56:57]
	s_waitcnt lgkmcnt(2)
	v_lshlrev_b32_e32 v53, 16, v89
	v_lshlrev_b32_e32 v52, 16, v88
	v_pk_mul_f32 v[50:51], v[50:51], v[52:53]
	v_pk_mul_f32 v[52:53], v[54:55], v[58:59]
	s_waitcnt lgkmcnt(0)
	v_lshlrev_b32_e32 v55, 16, v91
	v_lshlrev_b32_e32 v54, 16, v90
	v_pk_mul_f32 v[52:53], v[52:53], v[54:55]
	v_cvt_pk_bf16_f32 v50, v50, v51
	v_cvt_pk_bf16_f32 v51, v52, v53
	v_lshlrev_b32_e32 v52, 1, v78
	v_mad_u32_u24 v52, v167, s82, v52
	ds_write_b128 v52, v[44:47] offset:18432
	ds_write_b128 v52, v[48:51] offset:18448
	ds_read_b128 v[44:47], v152
	ds_read_b128 v[48:51], v188 offset:9216
	ds_read_b128 v[52:55], v152 offset:64
	ds_read_b128 v[56:59], v188 offset:9280
	s_waitcnt lgkmcnt(2)
	v_mfma_f32_16x16x32_bf16 v[48:51], v[44:47], v[48:51], 0
	ds_read_b128 v[60:63], v188 offset:11520
	ds_read_b128 v[88:91], v188 offset:11584
	ds_read_b128 v[92:95], v188 offset:13824
	ds_read_b128 v[96:99], v188 offset:13888
	ds_read_b128 v[100:103], v188 offset:16128
	ds_read_b128 v[104:107], v188 offset:16192
	s_waitcnt lgkmcnt(6)
	v_mfma_f32_16x16x32_bf16 v[48:51], v[52:55], v[56:59], v[48:51]
	v_mul_f32_e32 v111, 0x3fb8aa3b, v111
	s_waitcnt lgkmcnt(5)
	v_mfma_f32_16x16x32_bf16 v[60:63], v[44:47], v[60:63], 0
	s_waitcnt lgkmcnt(4)
	v_mfma_f32_16x16x32_bf16 v[56:59], v[52:55], v[88:91], v[60:63]
	s_nop 2
	v_mul_f32_e32 v48, v36, v48
	v_mul_f32_e32 v48, v72, v48
	v_mul_f32_e32 v48, v79, v48
	v_cvt_pk_bf16_f32 v48, v48, s0
	v_cndmask_b32_e64 v48, v48, 0, vcc
	ds_write_b16 v64, v48 offset:46080
	v_mul_f32_e32 v48, v37, v49
	v_mul_f32_e32 v48, v72, v48
	v_mul_f32_e32 v48, v80, v48
	v_cvt_pk_bf16_f32 v48, v48, s0
	v_cmp_ge_i32_e32 vcc, v169, v109
	s_waitcnt lgkmcnt(4)
	v_mfma_f32_16x16x32_bf16 v[92:95], v[44:47], v[92:95], 0
	v_cndmask_b32_e32 v48, 0, v48, vcc
	ds_write_b16 v64, v48 offset:46224
	v_mul_f32_e32 v48, v38, v50
	v_mul_f32_e32 v48, v72, v48
	v_mul_f32_e32 v48, v65, v48
	v_cvt_pk_bf16_f32 v48, v48, s0
	v_cmp_ge_i32_e32 vcc, v170, v109
	s_waitcnt lgkmcnt(4)
	v_mfma_f32_16x16x32_bf16 v[60:63], v[52:55], v[96:99], v[92:95]
	v_cndmask_b32_e32 v48, 0, v48, vcc
	ds_write_b16 v64, v48 offset:46368
	v_mul_f32_e32 v48, v39, v51
	v_mul_f32_e32 v48, v72, v48
	v_mul_f32_e32 v48, v66, v48
	v_cvt_pk_bf16_f32 v48, v48, s0
	v_cmp_ge_i32_e32 vcc, v171, v109
	s_waitcnt lgkmcnt(4)
	v_mfma_f32_16x16x32_bf16 v[44:47], v[44:47], v[100:103], 0
	v_cndmask_b32_e32 v48, 0, v48, vcc
	ds_write_b16 v64, v48 offset:46512
	v_mul_f32_e32 v48, v36, v56
	v_mul_f32_e32 v48, v73, v48
	v_mul_f32_e32 v48, v67, v48
	v_cvt_pk_bf16_f32 v48, v48, s0
	v_cndmask_b32_e64 v48, v48, 0, s[0:1]
	ds_write_b16 v64, v48 offset:46112
	v_mul_f32_e32 v48, v37, v57
	v_mul_f32_e32 v48, v73, v48
	v_mul_f32_e32 v48, v76, v48
	v_cvt_pk_bf16_f32 v48, v48, s0
	v_cmp_ge_i32_e32 vcc, v169, v172
	s_waitcnt lgkmcnt(5)
	v_mfma_f32_16x16x32_bf16 v[44:47], v[52:55], v[104:107], v[44:47]
	s_and_b32 s1, s94, 0xfffffc00
	v_cndmask_b32_e32 v48, 0, v48, vcc
	ds_write_b16 v64, v48 offset:46256
	v_mul_f32_e32 v48, v38, v58
	v_mul_f32_e32 v48, v73, v48
	v_mul_f32_e32 v48, v81, v48
	v_cvt_pk_bf16_f32 v48, v48, s0
	v_cmp_ge_i32_e32 vcc, v170, v172
	v_mul_f32_e32 v44, v36, v44
	v_mul_f32_e32 v44, v71, v44
	v_cndmask_b32_e32 v48, 0, v48, vcc
	ds_write_b16 v64, v48 offset:46400
	v_mul_f32_e32 v48, v39, v59
	v_mul_f32_e32 v48, v73, v48
	v_mul_f32_e32 v48, v77, v48
	v_cvt_pk_bf16_f32 v48, v48, s0
	v_cmp_ge_i32_e32 vcc, v171, v172
	v_mul_f32_e32 v44, v85, v44
	v_cvt_pk_bf16_f32 v44, v44, s0
	v_cndmask_b32_e32 v48, 0, v48, vcc
	ds_write_b16 v64, v48 offset:46544
	v_mul_f32_e32 v48, v36, v60
	v_mul_f32_e32 v48, v70, v48
	v_mul_f32_e32 v48, v82, v48
	v_cvt_pk_bf16_f32 v48, v48, s0
	v_cndmask_b32_e64 v48, v48, 0, s[4:5]
	ds_write_b16 v64, v48 offset:46144
	v_mul_f32_e32 v48, v37, v61
	v_mul_f32_e32 v48, v70, v48
	v_mul_f32_e32 v48, v83, v48
	v_cvt_pk_bf16_f32 v48, v48, s0
	v_cmp_ge_i32_e32 vcc, v169, v173
	v_cndmask_b32_e64 v44, v44, 0, s[6:7]
	ds_write_b16 v64, v44 offset:46176
	v_cndmask_b32_e32 v48, 0, v48, vcc
	ds_write_b16 v64, v48 offset:46288
	v_mul_f32_e32 v48, v38, v62
	v_mul_f32_e32 v48, v70, v48
	v_mul_f32_e32 v48, v84, v48
	v_cvt_pk_bf16_f32 v48, v48, s0
	v_cmp_ge_i32_e32 vcc, v170, v173
	v_mul_f32_e32 v44, v37, v45
	v_mul_f32_e32 v44, v71, v44
	v_cndmask_b32_e32 v48, 0, v48, vcc
	ds_write_b16 v64, v48 offset:46432
	v_mul_f32_e32 v48, v39, v63
	v_mul_f32_e32 v48, v70, v48
	v_mul_f32_e32 v48, v74, v48
	v_cvt_pk_bf16_f32 v48, v48, s0
	v_cmp_ge_i32_e32 vcc, v171, v173
	v_mul_f32_e32 v44, v86, v44
	v_cvt_pk_bf16_f32 v44, v44, s0
	v_cndmask_b32_e32 v48, 0, v48, vcc
	v_cmp_ge_i32_e32 vcc, v169, v174
	ds_write_b16 v64, v48 offset:46576
	v_mul_u32_u24_e32 v48, 0x48, v109
	v_cndmask_b32_e32 v44, 0, v44, vcc
	ds_write_b16 v64, v44 offset:46320
	v_mul_f32_e32 v44, v38, v46
	v_mul_f32_e32 v44, v71, v44
	v_mul_f32_e32 v44, v87, v44
	v_cvt_pk_bf16_f32 v44, v44, s0
	v_cmp_ge_i32_e32 vcc, v170, v174
	v_lshl_add_u32 v96, v48, 1, v68
	s_nop 0
	v_cndmask_b32_e32 v44, 0, v44, vcc
	ds_write_b16 v64, v44 offset:46464
	v_mul_f32_e32 v44, v39, v47
	v_mul_f32_e32 v44, v71, v44
	v_mul_f32_e32 v44, v75, v44
	v_cvt_pk_bf16_f32 v44, v44, s0
	v_cmp_ge_i32_e32 vcc, v171, v174
	s_lshl_b32 s0, s94, 7
	s_and_b32 s0, s0, 0x380
	v_cndmask_b32_e32 v44, 0, v44, vcc
	ds_write_b16 v64, v44 offset:46608
	s_waitcnt lgkmcnt(0)
	s_barrier
	ds_read_b128 v[44:47], v152 offset:18432
	ds_read_b128 v[48:51], v96 offset:27648
	ds_read_b128 v[56:59], v152 offset:18496
	ds_read_b128 v[52:55], v96 offset:27712
	ds_read_b128 v[64:67], v96 offset:36864
	ds_read_b128 v[68:71], v96 offset:36928
	ds_read_b128 v[76:79], v152 offset:46080
	ds_read_b128 v[176:179], v152 offset:46144
	ds_read_b128 v[80:83], v96 offset:29952
	ds_read_b128 v[84:87], v96 offset:30016
	ds_read_b128 v[92:95], v96 offset:39168
	ds_read_b128 v[184:187], v96 offset:39232
	s_waitcnt lgkmcnt(3)
	v_mfma_f32_16x16x32_bf16 v[88:91], v[44:47], v[80:83], 0
	s_or_b32 s0, s0, s1
	s_and_b32 s1, s68, 0x7f
	s_or_b32 s0, s0, s1
	s_waitcnt lgkmcnt(1)
	v_mfma_f32_16x16x32_bf16 v[188:191], v[44:47], v[92:95], 0
	s_cmpk_lt_i32 s68, 0x200
	s_cselect_b32 s0, s0, s94
	s_ashr_i32 s1, s0, 31
	v_mfma_f32_16x16x32_bf16 v[192:195], v[76:79], v[80:83], 0
	ds_read_b128 v[80:83], v96 offset:32256
	ds_read_b128 v[200:203], v96 offset:32320
	s_lshl_b64 s[4:5], s[0:1], 13
	v_cmp_eq_u32_e32 vcc, v168, v109
	v_mfma_f32_16x16x32_bf16 v[196:199], v[92:95], v[76:79], 0
	ds_read_b128 v[92:95], v96 offset:41472
	ds_read_b128 v[208:211], v96 offset:41536
	s_add_u32 s0, s77, s4
	s_addc_u32 s1, s78, s5
	s_waitcnt lgkmcnt(3)
	v_mfma_f32_16x16x32_bf16 v[204:207], v[44:47], v[80:83], 0
	s_add_u32 s6, s75, s4
	s_addc_u32 s7, s76, s5
	s_add_u32 s8, s29, s4
	s_waitcnt lgkmcnt(1)
	v_mfma_f32_16x16x32_bf16 v[212:215], v[44:47], v[92:95], 0
	s_addc_u32 s9, s74, s5
	s_add_u32 s4, s50, s4
	s_addc_u32 s5, s51, s5
	v_mfma_f32_16x16x32_bf16 v[216:219], v[76:79], v[80:83], 0
	ds_read_b128 v[80:83], v96 offset:34560
	ds_read_b128 v[224:227], v96 offset:34624
	s_mov_b32 s94, s93
	v_mfma_f32_16x16x32_bf16 v[220:223], v[92:95], v[76:79], 0
	ds_read_b128 v[92:95], v96 offset:43776
	ds_read_b128 v[232:235], v96 offset:43840
	v_mfma_f32_16x16x32_bf16 v[60:63], v[44:47], v[48:51], 0
	v_mfma_f32_16x16x32_bf16 v[72:75], v[44:47], v[64:67], 0
	v_mfma_f32_16x16x32_bf16 v[48:51], v[76:79], v[48:51], 0
	v_mfma_f32_16x16x32_bf16 v[64:67], v[64:67], v[76:79], 0
	s_waitcnt lgkmcnt(3)
	v_mfma_f32_16x16x32_bf16 v[228:231], v[44:47], v[80:83], 0
	v_mfma_f32_16x16x32_bf16 v[236:239], v[76:79], v[80:83], 0
	s_waitcnt lgkmcnt(1)
	v_mfma_f32_16x16x32_bf16 v[240:243], v[92:95], v[76:79], 0
	v_mfma_f32_16x16x32_bf16 v[80:83], v[56:59], v[184:187], v[188:191]
	v_mfma_f32_16x16x32_bf16 v[76:79], v[184:187], v[176:179], v[196:199]
	v_exp_f32_e32 v184, v111
	v_lshlrev_b32_e32 v185, 6, v168
	v_or_b32_e32 v152, v185, v109
	v_mfma_f32_16x16x32_bf16 v[44:47], v[44:47], v[92:95], 0
	v_cndmask_b32_e32 v111, 0, v184, vcc
	v_ashrrev_i32_e32 v153, 31, v152
	v_cmp_eq_u32_e32 vcc, v169, v109
	v_mfma_f32_16x16x32_bf16 v[104:107], v[56:59], v[52:55], v[60:63]
	v_cvt_pk_bf16_f32 v80, v80, v81
	v_cvt_pk_bf16_f32 v81, v82, v83
	v_cvt_pk_bf16_f32 v76, v76, v77
	v_mfma_f32_16x16x32_bf16 v[96:99], v[56:59], v[68:71], v[72:75]
	v_cvt_pk_bf16_f32 v77, v78, v79
	s_nop 2
	v_sub_f32_e32 v104, v111, v104
	v_cvt_pk_bf16_f32 v104, v104, s0
	v_mfma_f32_16x16x32_bf16 v[100:103], v[176:179], v[52:55], v[48:51]
	v_lshl_add_u32 v111, v109, 1, v175
	v_exp_f32_e32 v175, v40
	s_waitcnt vmcnt(5)
	v_mov_b64_e32 v[78:79], v[132:133]
	v_mfma_f32_16x16x32_bf16 v[92:95], v[68:71], v[176:179], v[64:67]
	v_mov_b32_e32 v82, v116
	v_mov_b32_e32 v83, v114
	v_mfma_f32_16x16x32_bf16 v[88:91], v[56:59], v[84:87], v[88:91]
	v_mfma_f32_16x16x32_bf16 v[84:87], v[176:179], v[84:87], v[192:195]
	v_mfma_f32_16x16x32_bf16 v[72:75], v[56:59], v[200:203], v[204:207]
	s_nop 1
	v_lshlrev_b32_e32 v192, 6, v169
	v_exp_f32_e32 v193, v41
	v_mfma_f32_16x16x32_bf16 v[60:63], v[56:59], v[208:211], v[212:215]
	v_mfma_f32_16x16x32_bf16 v[68:71], v[176:179], v[200:203], v[216:219]
	v_mfma_f32_16x16x32_bf16 v[64:67], v[208:211], v[176:179], v[220:223]
	s_nop 5
	v_cvt_pk_bf16_f32 v60, v60, v61
	v_cvt_pk_bf16_f32 v61, v62, v63
	s_waitcnt vmcnt(0)
	v_mov_b32_e32 v62, v148
	v_mfma_f32_16x16x32_bf16 v[52:55], v[56:59], v[224:227], v[228:231]
	s_waitcnt lgkmcnt(0)
	v_mfma_f32_16x16x32_bf16 v[44:47], v[56:59], v[232:235], v[44:47]
	v_mfma_f32_16x16x32_bf16 v[56:59], v[176:179], v[224:227], v[236:239]
	v_mfma_f32_16x16x32_bf16 v[48:51], v[232:235], v[176:179], v[240:243]
	v_lshlrev_b64 v[176:177], 1, v[152:153]
	v_lshl_add_u64 v[178:179], s[0:1], 0, v[176:177]
	global_store_short v[178:179], v104, off
	ds_read_u16 v40, v111
	ds_read_u16 v186, v111 offset:32
	ds_read_u16 v153, v111 offset:144
	ds_read_u16 v187, v111 offset:176
	ds_read_u16 v188, v111 offset:64
	ds_read_u16 v189, v111 offset:208
	ds_read_u16 v190, v111 offset:240
	ds_read_u16 v191, v111 offset:96
	s_waitcnt lgkmcnt(7)
	v_lshlrev_b32_e32 v40, 16, v40
	v_mul_f32_e32 v40, v36, v40
	v_fma_f32 v40, v175, v40, -v100
	v_cvt_pk_bf16_f32 v40, v40, s0
	v_lshl_add_u64 v[176:177], s[4:5], 0, v[176:177]
	global_store_short v[176:177], v40, off
	v_cndmask_b32_e32 v40, 0, v184, vcc
	v_or_b32_e32 v104, v192, v109
	v_sub_f32_e32 v40, v40, v105
	v_ashrrev_i32_e32 v105, 31, v104
	v_lshlrev_b64 v[176:177], 1, v[104:105]
	v_cvt_pk_bf16_f32 v40, v40, s0
	v_lshl_add_u64 v[178:179], s[0:1], 0, v[176:177]
	global_store_short v[178:179], v40, off
	s_waitcnt lgkmcnt(5)
	v_lshlrev_b32_e32 v40, 16, v153
	v_mul_f32_e32 v40, v37, v40
	v_fma_f32 v40, v193, v40, -v101
	v_cvt_pk_bf16_f32 v100, v40, s0
	v_lshl_add_u64 v[40:41], s[4:5], 0, v[176:177]
	v_cmp_eq_u32_e32 vcc, v170, v109
	global_store_short v[40:41], v100, off
	v_lshlrev_b32_e32 v178, 6, v170
	v_cndmask_b32_e32 v40, 0, v184, vcc
	v_sub_f32_e32 v40, v40, v106
	v_cvt_pk_bf16_f32 v105, v40, s0
	v_or_b32_e32 v40, v178, v109
	v_ashrrev_i32_e32 v41, 31, v40
	v_lshlrev_b64 v[100:101], 1, v[40:41]
	v_lshl_add_u64 v[176:177], s[0:1], 0, v[100:101]
	v_mul_f32_e32 v41, 0x3fb8aa3b, v42
	global_store_short v[176:177], v105, off
	v_exp_f32_e32 v179, v41
	ds_read_u16 v41, v111 offset:288
	ds_read_u16 v42, v111 offset:432
	ds_read_u16 v194, v111 offset:320
	ds_read_u16 v195, v111 offset:464
	ds_read_u16 v196, v111 offset:352
	ds_read_u16 v197, v111 offset:496
	ds_read_u16 v198, v111 offset:528
	ds_read_u16 v199, v111 offset:384
	s_waitcnt lgkmcnt(7)
	v_lshlrev_b32_e32 v41, 16, v41
	v_mul_f32_e32 v41, v38, v41
	v_fma_f32 v41, v179, v41, -v102
	v_cvt_pk_bf16_f32 v41, v41, s0
	v_lshl_add_u64 v[100:101], s[4:5], 0, v[100:101]
	v_lshlrev_b32_e32 v102, 6, v171
	global_store_short v[100:101], v41, off
	v_cmp_eq_u32_e32 vcc, v171, v109
	v_or_b32_e32 v100, v102, v109
	v_ashrrev_i32_e32 v101, 31, v100
	v_cndmask_b32_e32 v41, 0, v184, vcc
	v_sub_f32_e32 v41, v41, v107
	v_lshlrev_b64 v[106:107], 1, v[100:101]
	v_exp_f32_e32 v109, v43
	v_cvt_pk_bf16_f32 v41, v41, s0
	v_lshl_add_u64 v[176:177], s[0:1], 0, v[106:107]
	global_store_short v[176:177], v41, off
	s_waitcnt lgkmcnt(6)
	v_lshlrev_b32_e32 v41, 16, v42
	v_mul_f32_e32 v41, v39, v41
	v_fma_f32 v41, v109, v41, -v103
	v_cvt_pk_bf16_f32 v41, v41, s0
	v_lshl_add_u64 v[42:43], s[4:5], 0, v[106:107]
	v_ashrrev_i32_e32 v111, 31, v110
	global_store_short v[42:43], v41, off
	v_cvt_pk_bf16_f32 v42, v96, v97
	v_cvt_pk_bf16_f32 v43, v98, v99
	v_lshl_add_u64 v[96:97], v[110:111], 1, s[8:9]
	v_lshlrev_b32_e32 v41, 2, v167
	global_store_dwordx2 v[96:97], v[42:43], off
	v_cvt_pk_bf16_f32 v42, v92, v93
	v_lshl_or_b32 v92, v29, 10, v41
	v_ashrrev_i32_e32 v93, 31, v92
	v_cmp_eq_u32_e32 vcc, v168, v172
	v_cvt_pk_bf16_f32 v43, v94, v95
	v_lshl_add_u64 v[92:93], v[92:93], 1, s[6:7]
	v_cndmask_b32_e32 v29, 0, v184, vcc
	v_ashrrev_i32_e32 v153, 31, v185
	global_store_dwordx2 v[92:93], v[42:43], off
	v_sub_f32_e32 v29, v29, v88
	v_lshlrev_b64 v[42:43], 1, v[152:153]
	v_cvt_pk_bf16_f32 v29, v29, s0
	v_lshl_add_u64 v[94:95], s[0:1], 0, v[42:43]
	global_store_short v[94:95], v29, off offset:32
	v_lshlrev_b32_e32 v29, 16, v186
	v_mul_f32_e32 v29, v36, v29
	v_fma_f32 v29, v175, v29, -v84
	v_cvt_pk_bf16_f32 v29, v29, s0
	v_lshl_add_u64 v[42:43], s[4:5], 0, v[42:43]
	v_cmp_eq_u32_e32 vcc, v169, v172
	global_store_short v[42:43], v29, off offset:32
	v_ashrrev_i32_e32 v105, 31, v192
	v_cndmask_b32_e32 v29, 0, v184, vcc
	v_sub_f32_e32 v29, v29, v89
	v_lshlrev_b64 v[88:89], 1, v[104:105]
	v_cvt_pk_bf16_f32 v29, v29, s0
	v_lshl_add_u64 v[98:99], s[0:1], 0, v[88:89]
	global_store_short v[98:99], v29, off offset:32
	v_lshlrev_b32_e32 v29, 16, v187
	v_mul_f32_e32 v29, v37, v29
	v_fma_f32 v29, v193, v29, -v85
	v_cvt_pk_bf16_f32 v29, v29, s0
	v_lshl_add_u64 v[84:85], s[4:5], 0, v[88:89]
	v_cmp_eq_u32_e32 vcc, v170, v172
	global_store_short v[84:85], v29, off offset:32
	v_ashrrev_i32_e32 v41, 31, v178
	v_cndmask_b32_e32 v29, 0, v184, vcc
	v_sub_f32_e32 v29, v29, v90
	v_lshlrev_b64 v[40:41], 1, v[40:41]
	v_cvt_pk_bf16_f32 v29, v29, s0
	v_lshl_add_u64 v[88:89], s[0:1], 0, v[40:41]
	global_store_short v[88:89], v29, off offset:32
	s_waitcnt lgkmcnt(5)
	v_lshlrev_b32_e32 v29, 16, v194
	v_mul_f32_e32 v29, v38, v29
	v_fma_f32 v29, v179, v29, -v86
	v_cvt_pk_bf16_f32 v29, v29, s0
	v_lshl_add_u64 v[40:41], s[4:5], 0, v[40:41]
	v_cmp_eq_u32_e32 vcc, v171, v172
	global_store_short v[40:41], v29, off offset:32
	v_ashrrev_i32_e32 v101, 31, v102
	v_cndmask_b32_e32 v29, 0, v184, vcc
	v_sub_f32_e32 v29, v29, v91
	v_lshlrev_b64 v[90:91], 1, v[100:101]
	v_cvt_pk_bf16_f32 v29, v29, s0
	v_lshl_add_u64 v[100:101], s[0:1], 0, v[90:91]
	global_store_short v[100:101], v29, off offset:32
	s_waitcnt lgkmcnt(4)
	v_lshlrev_b32_e32 v29, 16, v195
	v_mul_f32_e32 v29, v39, v29
	v_fma_f32 v29, v109, v29, -v87
	v_cvt_pk_bf16_f32 v29, v29, s0
	v_lshl_add_u64 v[86:87], s[4:5], 0, v[90:91]
	v_cmp_eq_u32_e32 vcc, v168, v173
	global_store_short v[86:87], v29, off offset:32
	global_store_dwordx2 v[96:97], v[80:81], off offset:8
	v_cndmask_b32_e32 v29, 0, v184, vcc
	v_sub_f32_e32 v29, v29, v72
	v_cvt_pk_bf16_f32 v29, v29, s0
	global_store_dwordx2 v[92:93], v[76:77], off offset:512
	global_store_short v[94:95], v29, off offset:64
	v_lshlrev_b32_e32 v29, 16, v188
	v_mul_f32_e32 v29, v36, v29
	v_fma_f32 v29, v175, v29, -v68
	v_cvt_pk_bf16_f32 v29, v29, s0
	v_cmp_eq_u32_e32 vcc, v169, v173
	global_store_short v[42:43], v29, off offset:64
	v_mov_b32_e32 v77, v115
	v_cndmask_b32_e32 v29, 0, v184, vcc
	v_sub_f32_e32 v29, v29, v73
	v_cvt_pk_bf16_f32 v29, v29, s0
	global_store_short v[98:99], v29, off offset:64
	v_lshlrev_b32_e32 v29, 16, v189
	v_mul_f32_e32 v29, v37, v29
	v_fma_f32 v29, v193, v29, -v69
	v_cvt_pk_bf16_f32 v29, v29, s0
	v_cmp_eq_u32_e32 vcc, v170, v173
	global_store_short v[84:85], v29, off offset:64
	v_mov_b32_e32 v73, v117
	v_cndmask_b32_e32 v29, 0, v184, vcc
	v_sub_f32_e32 v29, v29, v74
	v_cvt_pk_bf16_f32 v29, v29, s0
	global_store_short v[88:89], v29, off offset:64
	s_waitcnt lgkmcnt(3)
	v_lshlrev_b32_e32 v29, 16, v196
	v_mul_f32_e32 v29, v38, v29
	v_fma_f32 v29, v179, v29, -v70
	v_cvt_pk_bf16_f32 v29, v29, s0
	v_cmp_eq_u32_e32 vcc, v171, v173
	global_store_short v[40:41], v29, off offset:64
	v_mov_b64_e32 v[90:91], v[130:131]
	v_cndmask_b32_e32 v29, 0, v184, vcc
	v_sub_f32_e32 v29, v29, v75
	v_cvt_pk_bf16_f32 v29, v29, s0
	global_store_short v[100:101], v29, off offset:64
	s_waitcnt lgkmcnt(2)
	v_lshlrev_b32_e32 v29, 16, v197
	v_mul_f32_e32 v29, v39, v29
	v_fma_f32 v29, v109, v29, -v71
	v_cvt_pk_bf16_f32 v29, v29, s0
	v_cmp_eq_u32_e32 vcc, v168, v174
	global_store_short v[86:87], v29, off offset:64
	global_store_dwordx2 v[96:97], v[60:61], off offset:16
	v_cndmask_b32_e32 v29, 0, v184, vcc
	v_sub_f32_e32 v29, v29, v52
	v_cvt_pk_bf16_f32 v60, v64, v65
	v_cvt_pk_bf16_f32 v61, v66, v67
	v_cvt_pk_bf16_f32 v29, v29, s0
	global_store_dwordx2 v[92:93], v[60:61], off offset:1024
	global_store_short v[94:95], v29, off offset:96
	v_lshlrev_b32_e32 v29, 16, v191
	v_mul_f32_e32 v29, v36, v29
	v_fma_f32 v29, v175, v29, -v56
	v_cvt_pk_bf16_f32 v29, v29, s0
	v_cmp_eq_u32_e32 vcc, v169, v174
	global_store_short v[42:43], v29, off offset:96
	v_cvt_pk_bf16_f32 v36, v44, v45
	v_cndmask_b32_e32 v29, 0, v184, vcc
	v_sub_f32_e32 v29, v29, v53
	v_cvt_pk_bf16_f32 v29, v29, s0
	global_store_short v[98:99], v29, off offset:96
	v_lshlrev_b32_e32 v29, 16, v190
	v_mul_f32_e32 v29, v37, v29
	v_fma_f32 v29, v193, v29, -v57
	v_cvt_pk_bf16_f32 v29, v29, s0
	v_cmp_eq_u32_e32 vcc, v170, v174
	global_store_short v[84:85], v29, off offset:96
	v_cvt_pk_bf16_f32 v37, v46, v47
	v_cndmask_b32_e32 v29, 0, v184, vcc
	v_sub_f32_e32 v29, v29, v54
	v_cvt_pk_bf16_f32 v29, v29, s0
	global_store_short v[88:89], v29, off offset:96
	s_waitcnt lgkmcnt(0)
	v_lshlrev_b32_e32 v29, 16, v199
	v_mul_f32_e32 v29, v38, v29
	v_fma_f32 v29, v179, v29, -v58
	v_cvt_pk_bf16_f32 v29, v29, s0
	v_cmp_eq_u32_e32 vcc, v171, v174
	global_store_short v[40:41], v29, off offset:96
	v_mov_b32_e32 v99, v164
	v_cndmask_b32_e32 v29, 0, v184, vcc
	v_sub_f32_e32 v29, v29, v55
	v_cvt_pk_bf16_f32 v29, v29, s0
	global_store_short v[100:101], v29, off offset:96
	v_lshlrev_b32_e32 v29, 16, v198
	v_mul_f32_e32 v29, v39, v29
	v_fma_f32 v29, v109, v29, -v59
	v_cvt_pk_bf16_f32 v29, v29, s0
	global_store_short v[86:87], v29, off offset:96
	global_store_dwordx2 v[96:97], v[36:37], off offset:24
	v_cvt_pk_bf16_f32 v36, v48, v49
	v_cvt_pk_bf16_f32 v37, v50, v51
	global_store_dwordx2 v[92:93], v[36:37], off offset:1536
	s_andn2_b64 vcc, exec, s[70:71]
	v_mov_b32_e32 v98, v163
	v_mov_b32_e32 v97, v165
	v_mov_b32_e32 v100, v166
	v_mov_b32_e32 v71, v113
	v_mov_b32_e32 v75, v31
	v_mov_b32_e32 v53, v125
	v_mov_b32_e32 v59, v123
	v_mov_b32_e32 v57, v129
	v_mov_b32_e32 v61, v127
	v_mov_b32_e32 v37, v141
	v_mov_b32_e32 v41, v139
	v_mov_b32_e32 v39, v145
	v_mov_b32_e32 v43, v143
	v_mov_b64_e32 v[86:87], v[120:121]
	v_mov_b64_e32 v[88:89], v[118:119]
	v_mov_b64_e32 v[68:69], v[134:135]
	v_mov_b64_e32 v[80:81], v[136:137]
	v_mov_b64_e32 v[50:51], v[150:151]
	v_mov_b64_e32 v[54:55], v[146:147]
	v_mov_b32_e32 v44, v144
	v_mov_b32_e32 v45, v142
	v_mov_b32_e32 v46, v140
	v_mov_b32_e32 v47, v138
	v_mov_b32_e32 v64, v128
	v_mov_b32_e32 v65, v126
	v_mov_b32_e32 v66, v124
	v_mov_b32_e32 v67, v122
	v_mov_b32_e32 v84, v112
	v_mov_b32_e32 v85, v30
	v_mov_b32_e32 v48, v149
	s_cbranch_vccz .LBB0_734

.LBB0_1029:
	s_cmpk_gt_i32 s2, 0xfff
	s_cbranch_scc1 .LBB0_1032
	s_waitcnt vmcnt(0)
	v_bfe_u32 v120, v181, 4, 2
	v_lshlrev_b32_e32 v120, 4, v120
	global_load_dwordx4 v[80:83], v120, s[40:41]
	global_load_dwordx4 v[84:87], v120, s[40:41] offset:64
	global_load_dwordx4 v[88:91], v120, s[40:41] offset:128
	global_load_dwordx4 v[92:95], v120, s[40:41] offset:192
	s_movk_i32 s8, 0x100
	s_movk_i32 s9, 0x1000
	s_add_i32 s39, s2, 0x400
	s_cmpk_lt_u32 s2, 0x100
	s_cselect_b32 s9, 0x500, s9
	s_cselect_b32 s39, s2, s39
	s_cmpk_eq_i32 s22, 0x200
	s_cselect_b32 s8, s8, s22
	s_cselect_b32 s9, s9, 0x1000
	s_cselect_b32 s39, s39, s2
.Lp4g_loop:
	s_lshr_b32 s0, s39, 3
	s_and_b32 s1, s39, 7
	s_lshr_b32 s4, s0, 7
	s_lshl_b32 s4, s4, 10
	s_lshl_b32 s5, s1, 7
	s_or_b32 s4, s4, s5
	s_and_b32 s5, s0, 0x7f
	s_or_b32 s4, s4, s5
	s_lshl_b32 s0, s0, 6
	s_lshl_b32 s4, s4, 13
	v_and_b32_e32 v104, 63, v181
	v_lshrrev_b32_e32 v105, 6, v181
	v_and_b32_e32 v106, 15, v181
	v_bfe_u32 v107, v181, 4, 2
	v_lshlrev_b32_e32 v108, 3, v104
	v_lshl_add_u32 v108, v105, 11, v108
	v_lshl_add_u32 v109, v105, 4, v106
	v_lshlrev_b32_e32 v109, 7, v109
	v_lshl_add_u32 v109, v107, 3, v109
	v_lshlrev_b32_e32 v110, 4, v181
	v_add_u32_e32 v111, 0x1000, v110
	v_lshlrev_b32_e32 v112, 5, v104
	v_lshl_add_u32 v113, v105, 4, s0
	v_add_u32_e32 v113, v113, v106
	v_lshlrev_b32_e32 v113, 13, v113
	v_lshl_add_u32 v113, v107, 3, v113
	s_lshl_b32 s5, s1, 7
	v_add_u32_e32 v113, s5, v113
	v_add_u32_e32 v114, 0xc00, v113
	s_add_u32 s6, s20, 0x15248000
	s_addc_u32 s7, s21, 0
	s_add_u32 s6, s6, s4
	s_addc_u32 s7, s7, 0
	global_load_dwordx2 v[16:17], v108, s[6:7]
	global_load_dwordx2 v[18:19], v108, s[6:7] offset:512
	global_load_dwordx2 v[20:21], v108, s[6:7] offset:1024
	global_load_dwordx2 v[22:23], v108, s[6:7] offset:1536
	s_add_u32 s6, s50, s4
	s_addc_u32 s7, s51, 0
	global_load_dwordx2 v[24:25], v109, s[6:7]
	global_load_dwordx2 v[26:27], v109, s[6:7] offset:32
	global_load_dwordx2 v[28:29], v109, s[6:7] offset:64
	global_load_dwordx2 v[30:31], v109, s[6:7] offset:96
	global_load_dwordx2 v[32:33], v114, s[20:21]
	global_load_dwordx2 v[34:35], v114, s[20:21] offset:32
	global_load_dwordx2 v[36:37], v114, s[20:21] offset:64
	global_load_dwordx2 v[38:39], v114, s[20:21] offset:96
	s_add_u32 s6, s20, 0x17348000
	s_addc_u32 s7, s21, 0
	s_add_u32 s6, s6, s4
	s_addc_u32 s7, s7, 0
	global_load_dwordx4 v[96:99], v110, s[6:7]
	global_load_dwordx4 v[100:103], v111, s[6:7]
	s_barrier
	s_waitcnt vmcnt(0)
	ds_write_b128 v110, v[96:99]
	ds_write_b128 v110, v[100:103] offset:4096
	s_waitcnt lgkmcnt(0)
	s_barrier
	v_lshlrev_b32_e32 v0, 16, v16
	v_and_b32_e32 v1, 0xffff0000, v16
	v_lshlrev_b32_e32 v2, 16, v17
	v_and_b32_e32 v3, 0xffff0000, v17
	v_lshlrev_b32_e32 v4, 16, v18
	v_and_b32_e32 v5, 0xffff0000, v18
	v_lshlrev_b32_e32 v6, 16, v19
	v_and_b32_e32 v7, 0xffff0000, v19
	v_lshlrev_b32_e32 v8, 16, v20
	v_and_b32_e32 v9, 0xffff0000, v20
	v_lshlrev_b32_e32 v10, 16, v21
	v_and_b32_e32 v11, 0xffff0000, v21
	v_lshlrev_b32_e32 v12, 16, v22
	v_and_b32_e32 v13, 0xffff0000, v22
	v_lshlrev_b32_e32 v14, 16, v23
	v_and_b32_e32 v15, 0xffff0000, v23
	ds_read_b64 v[48:49], v112 offset:0
	ds_read_b64 v[50:51], v112 offset:2048
	ds_read_b64 v[52:53], v112 offset:8
	ds_read_b64 v[54:55], v112 offset:2056
	ds_read_b64 v[56:57], v112 offset:16
	ds_read_b64 v[58:59], v112 offset:2064
	ds_read_b64 v[60:61], v112 offset:24
	ds_read_b64 v[62:63], v112 offset:2072
	s_waitcnt lgkmcnt(4)
	ds_read_b64 v[64:65], v112 offset:4096
	ds_read_b64 v[66:67], v112 offset:6144
	ds_read_b64 v[68:69], v112 offset:4104
	ds_read_b64 v[70:71], v112 offset:6152
	ds_read_b64 v[72:73], v112 offset:4112
	ds_read_b64 v[74:75], v112 offset:6160
	ds_read_b64 v[76:77], v112 offset:4120
	ds_read_b64 v[78:79], v112 offset:6168
	s_waitcnt lgkmcnt(0)
	s_waitcnt lgkmcnt(0)
	v_mfma_f32_16x16x32_bf16 v[0:3], v[48:51], v[24:27], v[0:3]
	v_mfma_f32_16x16x32_bf16 v[4:7], v[52:55], v[24:27], v[4:7]
	v_mfma_f32_16x16x32_bf16 v[8:11], v[56:59], v[24:27], v[8:11]
	v_mfma_f32_16x16x32_bf16 v[12:15], v[60:63], v[24:27], v[12:15]
	v_mfma_f32_16x16x32_bf16 v[0:3], v[64:67], v[28:31], v[0:3]
	v_mfma_f32_16x16x32_bf16 v[4:7], v[68:71], v[28:31], v[4:7]
	v_mfma_f32_16x16x32_bf16 v[8:11], v[72:75], v[28:31], v[8:11]
	v_mfma_f32_16x16x32_bf16 v[12:15], v[76:79], v[28:31], v[12:15]
	v_xor_b32_e32 v115, 16, v104
	v_xor_b32_e32 v116, 32, v104
	v_lshlrev_b32_e32 v115, 2, v115
	v_lshlrev_b32_e32 v116, 2, v116
	s_nop 4
	v_mul_f32_e32 v120, v0, v0
	v_fmac_f32_e32 v120, v1, v1
	v_fmac_f32_e32 v120, v2, v2
	v_fmac_f32_e32 v120, v3, v3
	v_fmac_f32_e32 v120, v4, v4
	v_fmac_f32_e32 v120, v5, v5
	v_fmac_f32_e32 v120, v6, v6
	v_fmac_f32_e32 v120, v7, v7
	v_fmac_f32_e32 v120, v8, v8
	v_fmac_f32_e32 v120, v9, v9
	v_fmac_f32_e32 v120, v10, v10
	v_fmac_f32_e32 v120, v11, v11
	v_fmac_f32_e32 v120, v12, v12
	v_fmac_f32_e32 v120, v13, v13
	v_fmac_f32_e32 v120, v14, v14
	v_fmac_f32_e32 v120, v15, v15
	ds_bpermute_b32 v121, v115, v120
	s_waitcnt lgkmcnt(0)
	v_add_f32_e32 v120, v120, v121
	ds_bpermute_b32 v121, v116, v120
	s_waitcnt lgkmcnt(0)
	v_add_f32_e32 v120, v120, v121
	v_mov_b32_e32 v122, 0x358637bd
	v_fmamk_f32 v120, v120, 0x3c800000, v122
	v_rsq_f32_e32 v120, v120
	v_lshlrev_b32_e32 v124, 16, v32
	v_and_b32_e32 v125, 0xffff0000, v32
	v_lshlrev_b32_e32 v126, 16, v33
	v_and_b32_e32 v127, 0xffff0000, v33
	v_mul_f32_e32 v128, 0xbfb8aa3b, v124
	v_mul_f32_e32 v129, 0xbfb8aa3b, v125
	v_mul_f32_e32 v130, 0xbfb8aa3b, v126
	v_mul_f32_e32 v131, 0xbfb8aa3b, v127
	v_exp_f32_e32 v128, v128
	v_exp_f32_e32 v129, v129
	v_exp_f32_e32 v130, v130
	v_exp_f32_e32 v131, v131
	v_mul_f32_e32 v132, v0, v120
	v_mul_f32_e32 v133, v1, v120
	v_mul_f32_e32 v134, v2, v120
	v_mul_f32_e32 v135, v3, v120
	v_add_f32_e32 v128, 1.0, v128
	v_add_f32_e32 v129, 1.0, v129
	v_add_f32_e32 v130, 1.0, v130
	v_add_f32_e32 v131, 1.0, v131
	v_rcp_f32_e32 v128, v128
	v_rcp_f32_e32 v129, v129
	v_rcp_f32_e32 v130, v130
	v_rcp_f32_e32 v131, v131
	v_mul_f32_e32 v132, v80, v132
	v_mul_f32_e32 v133, v81, v133
	v_mul_f32_e32 v134, v82, v134
	v_mul_f32_e32 v135, v83, v135
	v_mul_f32_e32 v128, v128, v124
	v_mul_f32_e32 v129, v129, v125
	v_mul_f32_e32 v130, v130, v126
	v_mul_f32_e32 v131, v131, v127
	v_mul_f32_e32 v132, v128, v132
	v_mul_f32_e32 v133, v129, v133
	v_mul_f32_e32 v134, v130, v134
	v_mul_f32_e32 v135, v131, v135
	v_cvt_pk_bf16_f32 v122, v132, v133
	v_cvt_pk_bf16_f32 v123, v134, v135
	global_store_dwordx2 v113, v[122:123], s[20:21]
	v_lshlrev_b32_e32 v124, 16, v34
	v_and_b32_e32 v125, 0xffff0000, v34
	v_lshlrev_b32_e32 v126, 16, v35
	v_and_b32_e32 v127, 0xffff0000, v35
	v_mul_f32_e32 v128, 0xbfb8aa3b, v124
	v_mul_f32_e32 v129, 0xbfb8aa3b, v125
	v_mul_f32_e32 v130, 0xbfb8aa3b, v126
	v_mul_f32_e32 v131, 0xbfb8aa3b, v127
	v_exp_f32_e32 v128, v128
	v_exp_f32_e32 v129, v129
	v_exp_f32_e32 v130, v130
	v_exp_f32_e32 v131, v131
	v_mul_f32_e32 v132, v4, v120
	v_mul_f32_e32 v133, v5, v120
	v_mul_f32_e32 v134, v6, v120
	v_mul_f32_e32 v135, v7, v120
	v_add_f32_e32 v128, 1.0, v128
	v_add_f32_e32 v129, 1.0, v129
	v_add_f32_e32 v130, 1.0, v130
	v_add_f32_e32 v131, 1.0, v131
	v_rcp_f32_e32 v128, v128
	v_rcp_f32_e32 v129, v129
	v_rcp_f32_e32 v130, v130
	v_rcp_f32_e32 v131, v131
	v_mul_f32_e32 v132, v84, v132
	v_mul_f32_e32 v133, v85, v133
	v_mul_f32_e32 v134, v86, v134
	v_mul_f32_e32 v135, v87, v135
	v_mul_f32_e32 v128, v128, v124
	v_mul_f32_e32 v129, v129, v125
	v_mul_f32_e32 v130, v130, v126
	v_mul_f32_e32 v131, v131, v127
	v_mul_f32_e32 v132, v128, v132
	v_mul_f32_e32 v133, v129, v133
	v_mul_f32_e32 v134, v130, v134
	v_mul_f32_e32 v135, v131, v135
	v_cvt_pk_bf16_f32 v122, v132, v133
	v_cvt_pk_bf16_f32 v123, v134, v135
	global_store_dwordx2 v113, v[122:123], s[20:21] offset:32
	v_lshlrev_b32_e32 v124, 16, v36
	v_and_b32_e32 v125, 0xffff0000, v36
	v_lshlrev_b32_e32 v126, 16, v37
	v_and_b32_e32 v127, 0xffff0000, v37
	v_mul_f32_e32 v128, 0xbfb8aa3b, v124
	v_mul_f32_e32 v129, 0xbfb8aa3b, v125
	v_mul_f32_e32 v130, 0xbfb8aa3b, v126
	v_mul_f32_e32 v131, 0xbfb8aa3b, v127
	v_exp_f32_e32 v128, v128
	v_exp_f32_e32 v129, v129
	v_exp_f32_e32 v130, v130
	v_exp_f32_e32 v131, v131
	v_mul_f32_e32 v132, v8, v120
	v_mul_f32_e32 v133, v9, v120
	v_mul_f32_e32 v134, v10, v120
	v_mul_f32_e32 v135, v11, v120
	v_add_f32_e32 v128, 1.0, v128
	v_add_f32_e32 v129, 1.0, v129
	v_add_f32_e32 v130, 1.0, v130
	v_add_f32_e32 v131, 1.0, v131
	v_rcp_f32_e32 v128, v128
	v_rcp_f32_e32 v129, v129
	v_rcp_f32_e32 v130, v130
	v_rcp_f32_e32 v131, v131
	v_mul_f32_e32 v132, v88, v132
	v_mul_f32_e32 v133, v89, v133
	v_mul_f32_e32 v134, v90, v134
	v_mul_f32_e32 v135, v91, v135
	v_mul_f32_e32 v128, v128, v124
	v_mul_f32_e32 v129, v129, v125
	v_mul_f32_e32 v130, v130, v126
	v_mul_f32_e32 v131, v131, v127
	v_mul_f32_e32 v132, v128, v132
	v_mul_f32_e32 v133, v129, v133
	v_mul_f32_e32 v134, v130, v134
	v_mul_f32_e32 v135, v131, v135
	v_cvt_pk_bf16_f32 v122, v132, v133
	v_cvt_pk_bf16_f32 v123, v134, v135
	global_store_dwordx2 v113, v[122:123], s[20:21] offset:64
	v_lshlrev_b32_e32 v124, 16, v38
	v_and_b32_e32 v125, 0xffff0000, v38
	v_lshlrev_b32_e32 v126, 16, v39
	v_and_b32_e32 v127, 0xffff0000, v39
	v_mul_f32_e32 v128, 0xbfb8aa3b, v124
	v_mul_f32_e32 v129, 0xbfb8aa3b, v125
	v_mul_f32_e32 v130, 0xbfb8aa3b, v126
	v_mul_f32_e32 v131, 0xbfb8aa3b, v127
	v_exp_f32_e32 v128, v128
	v_exp_f32_e32 v129, v129
	v_exp_f32_e32 v130, v130
	v_exp_f32_e32 v131, v131
	v_mul_f32_e32 v132, v12, v120
	v_mul_f32_e32 v133, v13, v120
	v_mul_f32_e32 v134, v14, v120
	v_mul_f32_e32 v135, v15, v120
	v_add_f32_e32 v128, 1.0, v128
	v_add_f32_e32 v129, 1.0, v129
	v_add_f32_e32 v130, 1.0, v130
	v_add_f32_e32 v131, 1.0, v131
	v_rcp_f32_e32 v128, v128
	v_rcp_f32_e32 v129, v129
	v_rcp_f32_e32 v130, v130
	v_rcp_f32_e32 v131, v131
	v_mul_f32_e32 v132, v92, v132
	v_mul_f32_e32 v133, v93, v133
	v_mul_f32_e32 v134, v94, v134
	v_mul_f32_e32 v135, v95, v135
	v_mul_f32_e32 v128, v128, v124
	v_mul_f32_e32 v129, v129, v125
	v_mul_f32_e32 v130, v130, v126
	v_mul_f32_e32 v131, v131, v127
	v_mul_f32_e32 v132, v128, v132
	v_mul_f32_e32 v133, v129, v133
	v_mul_f32_e32 v134, v130, v134
	v_mul_f32_e32 v135, v131, v135
	v_cvt_pk_bf16_f32 v122, v132, v133
	v_cvt_pk_bf16_f32 v123, v134, v135
	global_store_dwordx2 v113, v[122:123], s[20:21] offset:96
	s_add_i32 s39, s39, s8
	s_cmp_lt_i32 s39, s9
	s_cbranch_scc1 .Lp4g_loop

.LBB0_1085:
	s_or_b64 exec, exec, s[0:1]
	s_cmpk_gt_i32 s2, 0x8bf
	s_barrier
	s_cbranch_scc1 .LBB0_1096
	s_add_u32 s13, s20, 0x17348000
	s_addc_u32 s15, s21, 0
	s_add_u32 s29, s20, 0x15248000
	s_addc_u32 s39, s21, 0
	s_add_u32 s46, s50, 0x4200000
	s_addc_u32 s47, s51, 0
	s_add_u32 s56, s50, 0x2100000
	s_addc_u32 s57, s51, 0
	s_waitcnt vmcnt(27)
	v_mbcnt_hi_u32_b32 v40, -1, v183
	s_add_u32 s58, s20, 0x19448000
	v_and_b32_e32 v0, 64, v40
	s_addc_u32 s59, s21, 0
	s_lshl_b32 s60, s2, 7
	s_lshl_b32 s61, s22, 7
	s_movk_i32 s62, 0x6000
	s_mov_b32 s7, 0
	v_mov_b32_e32 v33, 0
	s_mov_b64 s[8:9], 0x1000
	s_mov_b64 s[10:11], 0x1800
	s_movk_i32 s63, 0x1000
	s_mov_b32 s12, 0x3c800000
	s_mov_b32 s14, 0x358637bd
	s_mov_b32 s64, 0x800000
	s_movk_i32 s65, 0x2000
	s_movk_i32 s66, 0x4000
	s_mov_b64 s[16:17], 0x1c00
	s_movk_i32 s67, 0x3000
	s_movk_i32 s68, 0x5000
	s_movk_i32 s69, 0x7000
	s_mov_b64 s[34:35], 0x80
	s_mov_b64 s[36:37], 0xc0
	s_brev_b32 s38, 60
	v_xor_b32_e32 v41, 1, v40
	v_add_u32_e32 v42, 64, v0
	v_xor_b32_e32 v43, 2, v40
	s_waitcnt vmcnt(26)
	v_xor_b32_e32 v44, 4, v40
	v_xor_b32_e32 v45, 8, v40
	s_mov_b32 s70, s2
	v_bfe_u32 v120, v181, 4, 2
	v_lshlrev_b32_e32 v120, 4, v120
	global_load_dwordx4 v[144:147], v120, s[40:41]
	global_load_dwordx4 v[148:151], v120, s[40:41] offset:64
	global_load_dwordx4 v[152:155], v120, s[40:41] offset:128
	global_load_dwordx4 v[156:159], v120, s[40:41] offset:192
	v_bfe_u32 v232, v181, 4, 2
	v_lshlrev_b32_e32 v232, 4, v232
	global_load_dwordx4 v[184:187], v232, s[44:45]
	global_load_dwordx4 v[188:191], v232, s[44:45] offset:64
	global_load_dwordx4 v[192:195], v232, s[44:45] offset:128
	global_load_dwordx4 v[196:199], v232, s[44:45] offset:192
	global_load_dwordx4 v[200:203], v232, s[44:45] offset:256
	global_load_dwordx4 v[204:207], v232, s[44:45] offset:320
	global_load_dwordx4 v[208:211], v232, s[44:45] offset:384
	global_load_dwordx4 v[212:215], v232, s[44:45] offset:448
	s_branch .LBB0_1089

.LBB0_1091:
	s_sub_i32 s4, s70, 0x840
	s_and_b32 s1, s4, 7
	s_lshr_b32 s0, s4, 3
	s_lshl_b32 s0, s0, 4
	s_add_i32 s0, s0, 0x8000
	s_add_i32 s4, s4, 0x1000
	s_lshl_b32 s4, s4, 13
	v_and_b32_e32 v104, 63, v181
	v_lshrrev_b32_e32 v105, 6, v181
	v_and_b32_e32 v106, 15, v181
	v_bfe_u32 v107, v181, 4, 2
	v_lshlrev_b32_e32 v108, 3, v104
	v_lshl_add_u32 v108, v105, 11, v108
	v_lshl_add_u32 v109, v105, 4, v106
	v_lshlrev_b32_e32 v109, 7, v109
	v_lshl_add_u32 v109, v107, 3, v109
	v_lshlrev_b32_e32 v110, 4, v181
	v_add_u32_e32 v111, 0x1000, v110
	v_lshlrev_b32_e32 v112, 5, v104
	v_lshl_add_u32 v113, v105, 4, s0
	v_add_u32_e32 v113, v113, v106
	v_lshlrev_b32_e32 v113, 13, v113
	v_lshl_add_u32 v113, v107, 3, v113
	s_lshl_b32 s5, s1, 7
	v_add_u32_e32 v113, s5, v113
	v_add_u32_e32 v114, 0xc00, v113
	s_add_u32 s24, s20, 0x15248000
	s_addc_u32 s25, s21, 0
	s_add_u32 s24, s24, s4
	s_addc_u32 s25, s25, 0
	global_load_dwordx2 v[16:17], v108, s[24:25]
	global_load_dwordx2 v[18:19], v108, s[24:25] offset:512
	global_load_dwordx2 v[20:21], v108, s[24:25] offset:1024
	global_load_dwordx2 v[22:23], v108, s[24:25] offset:1536
	s_add_u32 s24, s50, s4
	s_addc_u32 s25, s51, 0
	global_load_dwordx2 v[24:25], v109, s[24:25]
	global_load_dwordx2 v[26:27], v109, s[24:25] offset:32
	global_load_dwordx2 v[28:29], v109, s[24:25] offset:64
	global_load_dwordx2 v[30:31], v109, s[24:25] offset:96
	global_load_dwordx2 v[32:33], v114, s[20:21]
	global_load_dwordx2 v[34:35], v114, s[20:21] offset:32
	global_load_dwordx2 v[36:37], v114, s[20:21] offset:64
	global_load_dwordx2 v[38:39], v114, s[20:21] offset:96
	s_add_u32 s24, s20, 0x17348000
	s_addc_u32 s25, s21, 0
	s_add_u32 s24, s24, s4
	s_addc_u32 s25, s25, 0
	global_load_dwordx4 v[96:99], v110, s[24:25]
	global_load_dwordx4 v[100:103], v111, s[24:25]
	s_barrier
	s_waitcnt vmcnt(0)
	ds_write_b128 v110, v[96:99]
	ds_write_b128 v110, v[100:103] offset:4096
	s_waitcnt lgkmcnt(0)
	s_barrier
	v_cmp_gt_u32_e32 vcc, 1, v105
	s_and_saveexec_b64 s[42:43], vcc
	s_cbranch_execz .Lp4s_done
	v_lshlrev_b32_e32 v0, 16, v16
	v_and_b32_e32 v1, 0xffff0000, v16
	v_lshlrev_b32_e32 v2, 16, v17
	v_and_b32_e32 v3, 0xffff0000, v17
	v_lshlrev_b32_e32 v4, 16, v18
	v_and_b32_e32 v5, 0xffff0000, v18
	v_lshlrev_b32_e32 v6, 16, v19
	v_and_b32_e32 v7, 0xffff0000, v19
	v_lshlrev_b32_e32 v8, 16, v20
	v_and_b32_e32 v9, 0xffff0000, v20
	v_lshlrev_b32_e32 v10, 16, v21
	v_and_b32_e32 v11, 0xffff0000, v21
	v_lshlrev_b32_e32 v12, 16, v22
	v_and_b32_e32 v13, 0xffff0000, v22
	v_lshlrev_b32_e32 v14, 16, v23
	v_and_b32_e32 v15, 0xffff0000, v23
	ds_read_b64 v[48:49], v112 offset:0
	ds_read_b64 v[50:51], v112 offset:2048
	ds_read_b64 v[52:53], v112 offset:8
	ds_read_b64 v[54:55], v112 offset:2056
	ds_read_b64 v[56:57], v112 offset:16
	ds_read_b64 v[58:59], v112 offset:2064
	ds_read_b64 v[60:61], v112 offset:24
	ds_read_b64 v[62:63], v112 offset:2072
	s_waitcnt lgkmcnt(4)
	ds_read_b64 v[64:65], v112 offset:4096
	ds_read_b64 v[66:67], v112 offset:6144
	ds_read_b64 v[68:69], v112 offset:4104
	ds_read_b64 v[70:71], v112 offset:6152
	ds_read_b64 v[72:73], v112 offset:4112
	ds_read_b64 v[74:75], v112 offset:6160
	ds_read_b64 v[76:77], v112 offset:4120
	ds_read_b64 v[78:79], v112 offset:6168
	s_waitcnt lgkmcnt(0)
	s_waitcnt lgkmcnt(0)
	v_mfma_f32_16x16x32_bf16 v[0:3], v[48:51], v[24:27], v[0:3]
	v_mfma_f32_16x16x32_bf16 v[4:7], v[52:55], v[24:27], v[4:7]
	v_mfma_f32_16x16x32_bf16 v[8:11], v[56:59], v[24:27], v[8:11]
	v_mfma_f32_16x16x32_bf16 v[12:15], v[60:63], v[24:27], v[12:15]
	v_mfma_f32_16x16x32_bf16 v[0:3], v[64:67], v[28:31], v[0:3]
	v_mfma_f32_16x16x32_bf16 v[4:7], v[68:71], v[28:31], v[4:7]
	v_mfma_f32_16x16x32_bf16 v[8:11], v[72:75], v[28:31], v[8:11]
	v_mfma_f32_16x16x32_bf16 v[12:15], v[76:79], v[28:31], v[12:15]
	v_xor_b32_e32 v115, 16, v104
	v_xor_b32_e32 v116, 32, v104
	v_lshlrev_b32_e32 v115, 2, v115
	v_lshlrev_b32_e32 v116, 2, v116
	s_nop 4
	v_mul_f32_e32 v120, v0, v0
	v_fmac_f32_e32 v120, v1, v1
	v_fmac_f32_e32 v120, v2, v2
	v_fmac_f32_e32 v120, v3, v3
	v_fmac_f32_e32 v120, v4, v4
	v_fmac_f32_e32 v120, v5, v5
	v_fmac_f32_e32 v120, v6, v6
	v_fmac_f32_e32 v120, v7, v7
	v_fmac_f32_e32 v120, v8, v8
	v_fmac_f32_e32 v120, v9, v9
	v_fmac_f32_e32 v120, v10, v10
	v_fmac_f32_e32 v120, v11, v11
	v_fmac_f32_e32 v120, v12, v12
	v_fmac_f32_e32 v120, v13, v13
	v_fmac_f32_e32 v120, v14, v14
	v_fmac_f32_e32 v120, v15, v15
	ds_bpermute_b32 v121, v115, v120
	s_waitcnt lgkmcnt(0)
	v_add_f32_e32 v120, v120, v121
	ds_bpermute_b32 v121, v116, v120
	s_waitcnt lgkmcnt(0)
	v_add_f32_e32 v120, v120, v121
	v_mov_b32_e32 v122, 0x358637bd
	v_fmamk_f32 v120, v120, 0x3c800000, v122
	v_rsq_f32_e32 v120, v120
	v_lshlrev_b32_e32 v124, 16, v32
	v_and_b32_e32 v125, 0xffff0000, v32
	v_lshlrev_b32_e32 v126, 16, v33
	v_and_b32_e32 v127, 0xffff0000, v33
	v_mul_f32_e32 v128, 0xbfb8aa3b, v124
	v_mul_f32_e32 v129, 0xbfb8aa3b, v125
	v_mul_f32_e32 v130, 0xbfb8aa3b, v126
	v_mul_f32_e32 v131, 0xbfb8aa3b, v127
	v_exp_f32_e32 v128, v128
	v_exp_f32_e32 v129, v129
	v_exp_f32_e32 v130, v130
	v_exp_f32_e32 v131, v131
	v_mul_f32_e32 v132, v0, v120
	v_mul_f32_e32 v133, v1, v120
	v_mul_f32_e32 v134, v2, v120
	v_mul_f32_e32 v135, v3, v120
	v_add_f32_e32 v128, 1.0, v128
	v_add_f32_e32 v129, 1.0, v129
	v_add_f32_e32 v130, 1.0, v130
	v_add_f32_e32 v131, 1.0, v131
	v_rcp_f32_e32 v128, v128
	v_rcp_f32_e32 v129, v129
	v_rcp_f32_e32 v130, v130
	v_rcp_f32_e32 v131, v131
	v_mul_f32_e32 v132, v144, v132
	v_mul_f32_e32 v133, v145, v133
	v_mul_f32_e32 v134, v146, v134
	v_mul_f32_e32 v135, v147, v135
	v_mul_f32_e32 v128, v128, v124
	v_mul_f32_e32 v129, v129, v125
	v_mul_f32_e32 v130, v130, v126
	v_mul_f32_e32 v131, v131, v127
	v_mul_f32_e32 v132, v128, v132
	v_mul_f32_e32 v133, v129, v133
	v_mul_f32_e32 v134, v130, v134
	v_mul_f32_e32 v135, v131, v135
	v_cvt_pk_bf16_f32 v122, v132, v133
	v_cvt_pk_bf16_f32 v123, v134, v135
	global_store_dwordx2 v113, v[122:123], s[20:21]
	v_lshlrev_b32_e32 v124, 16, v34
	v_and_b32_e32 v125, 0xffff0000, v34
	v_lshlrev_b32_e32 v126, 16, v35
	v_and_b32_e32 v127, 0xffff0000, v35
	v_mul_f32_e32 v128, 0xbfb8aa3b, v124
	v_mul_f32_e32 v129, 0xbfb8aa3b, v125
	v_mul_f32_e32 v130, 0xbfb8aa3b, v126
	v_mul_f32_e32 v131, 0xbfb8aa3b, v127
	v_exp_f32_e32 v128, v128
	v_exp_f32_e32 v129, v129
	v_exp_f32_e32 v130, v130
	v_exp_f32_e32 v131, v131
	v_mul_f32_e32 v132, v4, v120
	v_mul_f32_e32 v133, v5, v120
	v_mul_f32_e32 v134, v6, v120
	v_mul_f32_e32 v135, v7, v120
	v_add_f32_e32 v128, 1.0, v128
	v_add_f32_e32 v129, 1.0, v129
	v_add_f32_e32 v130, 1.0, v130
	v_add_f32_e32 v131, 1.0, v131
	v_rcp_f32_e32 v128, v128
	v_rcp_f32_e32 v129, v129
	v_rcp_f32_e32 v130, v130
	v_rcp_f32_e32 v131, v131
	v_mul_f32_e32 v132, v148, v132
	v_mul_f32_e32 v133, v149, v133
	v_mul_f32_e32 v134, v150, v134
	v_mul_f32_e32 v135, v151, v135
	v_mul_f32_e32 v128, v128, v124
	v_mul_f32_e32 v129, v129, v125
	v_mul_f32_e32 v130, v130, v126
	v_mul_f32_e32 v131, v131, v127
	v_mul_f32_e32 v132, v128, v132
	v_mul_f32_e32 v133, v129, v133
	v_mul_f32_e32 v134, v130, v134
	v_mul_f32_e32 v135, v131, v135
	v_cvt_pk_bf16_f32 v122, v132, v133
	v_cvt_pk_bf16_f32 v123, v134, v135
	global_store_dwordx2 v113, v[122:123], s[20:21] offset:32
	v_lshlrev_b32_e32 v124, 16, v36
	v_and_b32_e32 v125, 0xffff0000, v36
	v_lshlrev_b32_e32 v126, 16, v37
	v_and_b32_e32 v127, 0xffff0000, v37
	v_mul_f32_e32 v128, 0xbfb8aa3b, v124
	v_mul_f32_e32 v129, 0xbfb8aa3b, v125
	v_mul_f32_e32 v130, 0xbfb8aa3b, v126
	v_mul_f32_e32 v131, 0xbfb8aa3b, v127
	v_exp_f32_e32 v128, v128
	v_exp_f32_e32 v129, v129
	v_exp_f32_e32 v130, v130
	v_exp_f32_e32 v131, v131
	v_mul_f32_e32 v132, v8, v120
	v_mul_f32_e32 v133, v9, v120
	v_mul_f32_e32 v134, v10, v120
	v_mul_f32_e32 v135, v11, v120
	v_add_f32_e32 v128, 1.0, v128
	v_add_f32_e32 v129, 1.0, v129
	v_add_f32_e32 v130, 1.0, v130
	v_add_f32_e32 v131, 1.0, v131
	v_rcp_f32_e32 v128, v128
	v_rcp_f32_e32 v129, v129
	v_rcp_f32_e32 v130, v130
	v_rcp_f32_e32 v131, v131
	v_mul_f32_e32 v132, v152, v132
	v_mul_f32_e32 v133, v153, v133
	v_mul_f32_e32 v134, v154, v134
	v_mul_f32_e32 v135, v155, v135
	v_mul_f32_e32 v128, v128, v124
	v_mul_f32_e32 v129, v129, v125
	v_mul_f32_e32 v130, v130, v126
	v_mul_f32_e32 v131, v131, v127
	v_mul_f32_e32 v132, v128, v132
	v_mul_f32_e32 v133, v129, v133
	v_mul_f32_e32 v134, v130, v134
	v_mul_f32_e32 v135, v131, v135
	v_cvt_pk_bf16_f32 v122, v132, v133
	v_cvt_pk_bf16_f32 v123, v134, v135
	global_store_dwordx2 v113, v[122:123], s[20:21] offset:64
	v_lshlrev_b32_e32 v124, 16, v38
	v_and_b32_e32 v125, 0xffff0000, v38
	v_lshlrev_b32_e32 v126, 16, v39
	v_and_b32_e32 v127, 0xffff0000, v39
	v_mul_f32_e32 v128, 0xbfb8aa3b, v124
	v_mul_f32_e32 v129, 0xbfb8aa3b, v125
	v_mul_f32_e32 v130, 0xbfb8aa3b, v126
	v_mul_f32_e32 v131, 0xbfb8aa3b, v127
	v_exp_f32_e32 v128, v128
	v_exp_f32_e32 v129, v129
	v_exp_f32_e32 v130, v130
	v_exp_f32_e32 v131, v131
	v_mul_f32_e32 v132, v12, v120
	v_mul_f32_e32 v133, v13, v120
	v_mul_f32_e32 v134, v14, v120
	v_mul_f32_e32 v135, v15, v120
	v_add_f32_e32 v128, 1.0, v128
	v_add_f32_e32 v129, 1.0, v129
	v_add_f32_e32 v130, 1.0, v130
	v_add_f32_e32 v131, 1.0, v131
	v_rcp_f32_e32 v128, v128
	v_rcp_f32_e32 v129, v129
	v_rcp_f32_e32 v130, v130
	v_rcp_f32_e32 v131, v131
	v_mul_f32_e32 v132, v156, v132
	v_mul_f32_e32 v133, v157, v133
	v_mul_f32_e32 v134, v158, v134
	v_mul_f32_e32 v135, v159, v135
	v_mul_f32_e32 v128, v128, v124
	v_mul_f32_e32 v129, v129, v125
	v_mul_f32_e32 v130, v130, v126
	v_mul_f32_e32 v131, v131, v127
	v_mul_f32_e32 v132, v128, v132
	v_mul_f32_e32 v133, v129, v133
	v_mul_f32_e32 v134, v130, v134
	v_mul_f32_e32 v135, v131, v135
	v_cvt_pk_bf16_f32 v122, v132, v133
	v_cvt_pk_bf16_f32 v123, v134, v135
	global_store_dwordx2 v113, v[122:123], s[20:21] offset:96
.Lp4s_done:
	s_or_b64 exec, exec, s[42:43]
	s_branch .LBB0_1088
